# P1/P4 unit headers: group height is always 8 for this shape, generic division (rcp + readfirstlane + corrections) replaced by shift/mask (58 instructions fewer per header pair)
# speedup vs baseline: 1.0006x; 1.0006x over previous
;     __device__ __forceinline__ bool next(int i, Unit& u) const { if (i >= count) return false; const int L = first + i; u.pm = L / nN; u.pn = L % nN; return true; }
;     __host__ __device__ bool next(int i, Unit& u) const {
;         const long L = (long)i * G + c; if (L >= nwg) return false;
;         int wgid = (int)L; { const int q = nwg / NXCD, r = nwg % NXCD, xcd = wgid % NXCD, off = wgid / NXCD; wgid = (xcd < r ? xcd * (q + 1) : r * (q + 1) + (xcd - r) * q) + off; }
;         const int nig = WGM * nN, gid = wgid / nig, fm = gid * WGM, gsz = (nM - fm) < WGM ? (nM - fm) : WGM;
;         u.pm = fm + ((wgid % nig) % gsz); u.pn = (wgid % nig) / gsz; return true;
;     }
.LBB0_227:
	s_add_i32 s67, s67, 1
	s_mul_i32 s1, s67, s31
	s_mul_hi_u32 s2, s67, s69
	s_add_i32 s2, s2, s1
	s_mul_i32 s1, s67, s69
	s_add_u32 s8, s1, s10
	s_addc_u32 s9, s2, s33
	v_cmp_gt_i64_e64 s[4:5], s[8:9], v[196:197]
	v_cmp_lt_i64_e64 s[2:3], s[8:9], v[194:195]
	s_and_b64 vcc, exec, s[4:5]
	s_cbranch_vccnz .LBB0_229
	s_ashr_i32 s0, s8, 31
	s_lshr_b32 s0, s0, 29
	s_add_i32 s0, s8, s0
	s_ashr_i32 s1, s0, 3
	s_and_b32 s0, s0, -8
	s_sub_i32 s0, s8, s0
	s_cmp_lt_i32 s0, 0
	s_movk_i32 s8, 0x51
	s_cselect_b32 s8, s8, 0x50
	s_mul_i32 s0, s0, s8
	s_add_i32 s0, s0, s1
	s_mul_hi_i32 s1, s0, 0x66666667
	s_lshr_b32 s8, s1, 31
	s_ashr_i32 s1, s1, 5
	s_add_i32 s1, s1, s8
	s_lshl_b32 s8, s1, 3
	s_mulk_i32 s1, 0x50
	s_sub_i32 s1, s0, s1
	s_lshr_b32 s0, s1, 3
	s_and_b32 s1, s1, 7
	s_add_i32 s52, s8, s1

;     __device__ __forceinline__ bool next(int i, Unit& u) const { if (i >= count) return false; const int L = first + i; u.pm = L / nN; u.pn = L % nN; return true; }
;     __host__ __device__ bool next(int i, Unit& u) const {
;         const long L = (long)i * G + c; if (L >= nwg) return false;
;         int wgid = (int)L; { const int q = nwg / NXCD, r = nwg % NXCD, xcd = wgid % NXCD, off = wgid / NXCD; wgid = (xcd < r ? xcd * (q + 1) : r * (q + 1) + (xcd - r) * q) + off; }
;         const int nig = WGM * nN, gid = wgid / nig, fm = gid * WGM, gsz = (nM - fm) < WGM ? (nM - fm) : WGM;
;         u.pm = fm + ((wgid % nig) % gsz); u.pn = (wgid % nig) / gsz; return true;
;     }
.LBB0_839:
	s_add_i32 s29, s29, 1
	s_mul_i32 s2, s29, s33
	s_mul_hi_u32 s3, s29, s69
	s_add_i32 s3, s3, s2
	s_mul_i32 s2, s29, s69
	s_add_u32 s24, s2, s10
	s_addc_u32 s25, s3, s15
	v_cmp_gt_i64_e64 s[4:5], s[24:25], v[196:197]
	v_cmp_lt_i64_e64 s[2:3], s[24:25], v[194:195]
	s_and_b64 vcc, exec, s[4:5]
	s_cbranch_vccnz .LBB0_841
	s_ashr_i32 s25, s24, 31
	s_lshr_b32 s25, s25, 29
	s_add_i32 s25, s24, s25
	s_ashr_i32 s26, s25, 3
	s_and_b32 s25, s25, -8
	s_sub_i32 s24, s24, s25
	s_cmp_lt_i32 s24, 0
	s_cselect_b32 s25, s28, 0xb0
	s_mul_i32 s24, s24, s25
	s_add_i32 s24, s24, s26
	s_mul_hi_i32 s25, s24, 0x2e8ba2e9
	s_lshr_b32 s26, s25, 31
	s_ashr_i32 s25, s25, 5
	s_add_i32 s25, s25, s26
	s_lshl_b32 s26, s25, 3
	s_mulk_i32 s25, 0xb0
	s_sub_i32 s24, s24, s25
	s_lshr_b32 s38, s24, 3
	s_and_b32 s24, s24, 7
	s_add_i32 s40, s26, s24
